# nt on more read-once loads: final_rows bf16 input rows, t2_rows partial outputs and lse, dilated-attention Q rows
# baseline (speedup 1.0000x reference)
; DI void final_rows(const bf16_t* x, const sq_t* sq, const float* g, float* out, int nrows, int gw, int NGW, int lane) {
;     for (int row0 = gw; row0 < nrows; row0 += 4 * NGW) {
;         u32x2 v[4][4]; float rstd[4];
; #pragma unroll
;         for (int u = 0; u < 4; ++u) { const int row = row0 + u * NGW; if (row < nrows) { const u32x2* xr = (const u32x2*)(x + (size_t)row * 1024) + lane;
; #pragma unroll
;                 for (int j = 0; j < 4; ++j) v[u][j] = xr[64 * j];
;                 rstd[u] = 1.f / sqrtf((float)sq[row] * (1.f / 1024.f / 16777216.f) + RMS_EPS); } }
.LBB0_369:
	s_ashr_i32 s19, s18, 31
	s_lshl_b64 s[6:7], s[18:19], 11
	s_lshl_b64 s[16:17], s[18:19], 3
	s_add_u32 s20, s3, s16
	s_addc_u32 s21, s13, s17
	global_load_dwordx2 v[44:45], v149, s[20:21]
	v_lshl_add_u64 v[36:37], v[6:7], 0, s[6:7]
	global_load_dwordx2 v[42:43], v[36:37], off nt
	global_load_dwordx2 v[40:41], v[36:37], off offset:512 nt
	global_load_dwordx2 v[38:39], v[36:37], off offset:1024 nt
	s_nop 0
	global_load_dwordx2 v[36:37], v[36:37], off offset:1536 nt
	s_add_i32 s16, s18, s94
	s_cmpk_lt_i32 s16, 0x4000
	s_cselect_b64 s[24:25], -1, 0
	s_cmpk_gt_i32 s16, 0x3fff
	s_waitcnt vmcnt(4)
	v_ffbh_u32_e32 v0, v45
	v_min_u32_e32 v0, 32, v0
	v_lshlrev_b64 v[44:45], v0, v[44:45]
	v_min_u32_e32 v44, 1, v44
	v_or_b32_e32 v44, v45, v44
	v_cvt_f32_u32_e32 v44, v44
	v_sub_u32_e32 v0, 32, v0
	v_ldexp_f32 v0, v44, v0
	v_fmamk_f32 v0, v0, 0x2e800000, v206
	v_mul_f32_e32 v44, 0x4f800000, v0
	v_cmp_gt_f32_e32 vcc, s80, v0
	s_nop 1
	v_cndmask_b32_e32 v0, v0, v44, vcc
	v_sqrt_f32_e32 v44, v0
	s_nop 0
	v_add_u32_e32 v45, -1, v44
	v_add_u32_e32 v46, 1, v44
	v_fma_f32 v47, -v45, v44, v0
	v_fma_f32 v48, -v46, v44, v0
	v_cmp_ge_f32_e64 s[6:7], 0, v47
	s_nop 1
	v_cndmask_b32_e64 v44, v44, v45, s[6:7]
	v_cmp_lt_f32_e64 s[6:7], 0, v48
	s_nop 1
	v_cndmask_b32_e64 v44, v44, v46, s[6:7]
	v_mul_f32_e32 v45, 0x37800000, v44
	v_cndmask_b32_e32 v44, v44, v45, vcc
	v_cmp_class_f32_e32 vcc, v0, v207
	s_nop 1
	v_cndmask_b32_e32 v0, v44, v0, vcc
	v_div_scale_f32 v44, s[6:7], v0, v0, 1.0
	v_rcp_f32_e32 v45, v44
	v_div_scale_f32 v46, vcc, 1.0, v0, 1.0
	v_fma_f32 v47, -v44, v45, 1.0
	v_fmac_f32_e32 v45, v47, v45
	v_mul_f32_e32 v47, v46, v45
	v_fma_f32 v48, -v44, v47, v46
	v_fmac_f32_e32 v47, v48, v45
	v_fma_f32 v44, -v44, v47, v46
	v_div_fmas_f32 v44, v44, v45, v47
	v_div_fixup_f32 v0, v44, v0, 1.0
	s_cbranch_scc1 .LBB0_371
	s_ashr_i32 s17, s16, 31
	s_lshl_b64 s[6:7], s[16:17], 11
	s_lshl_b64 s[22:23], s[94:95], 3
	s_add_u32 s20, s20, s22
	s_addc_u32 s21, s21, s23
	global_load_dwordx2 v[44:45], v149, s[20:21]
	v_lshl_add_u64 v[28:29], v[6:7], 0, s[6:7]
	global_load_dwordx2 v[34:35], v[28:29], off nt
	global_load_dwordx2 v[32:33], v[28:29], off offset:512 nt
	global_load_dwordx2 v[30:31], v[28:29], off offset:1024 nt
	s_nop 0
	global_load_dwordx2 v[28:29], v[28:29], off offset:1536 nt
	s_waitcnt vmcnt(4)
	v_ffbh_u32_e32 v1, v45
	v_min_u32_e32 v1, 32, v1
	v_lshlrev_b64 v[44:45], v1, v[44:45]
	v_min_u32_e32 v44, 1, v44
	v_or_b32_e32 v44, v45, v44
	v_cvt_f32_u32_e32 v44, v44
	v_sub_u32_e32 v1, 32, v1
	v_ldexp_f32 v1, v44, v1
	v_fmamk_f32 v1, v1, 0x2e800000, v206
	v_mul_f32_e32 v44, 0x4f800000, v1
	v_cmp_gt_f32_e32 vcc, s80, v1
	s_nop 1
	v_cndmask_b32_e32 v1, v1, v44, vcc
	v_sqrt_f32_e32 v44, v1
	s_nop 0
	v_add_u32_e32 v45, -1, v44
	v_add_u32_e32 v46, 1, v44
	v_fma_f32 v47, -v45, v44, v1
	v_fma_f32 v48, -v46, v44, v1
	v_cmp_ge_f32_e64 s[6:7], 0, v47
	s_nop 1
	v_cndmask_b32_e64 v44, v44, v45, s[6:7]
	v_cmp_lt_f32_e64 s[6:7], 0, v48
	s_nop 1
	v_cndmask_b32_e64 v44, v44, v46, s[6:7]
	v_mul_f32_e32 v45, 0x37800000, v44
	v_cndmask_b32_e32 v44, v44, v45, vcc
	v_cmp_class_f32_e32 vcc, v1, v207
	s_nop 1
	v_cndmask_b32_e32 v1, v44, v1, vcc
	v_div_scale_f32 v44, s[6:7], v1, v1, 1.0
	v_rcp_f32_e32 v45, v44
	v_div_scale_f32 v46, vcc, 1.0, v1, 1.0
	v_fma_f32 v47, -v44, v45, 1.0
	v_fmac_f32_e32 v45, v47, v45
	v_mul_f32_e32 v47, v46, v45
	v_fma_f32 v48, -v44, v47, v46
	v_fmac_f32_e32 v47, v48, v45
	v_fma_f32 v44, -v44, v47, v46
	v_div_fmas_f32 v44, v44, v45, v47
	v_div_fixup_f32 v1, v44, v1, 1.0
; DI void final_rows(const bf16_t* x, const sq_t* sq, const float* g, float* out, int nrows, int gw, int NGW, int lane) {
;     for (int row0 = gw; row0 < nrows; row0 += 4 * NGW) {
;         u32x2 v[4][4]; float rstd[4];
; #pragma unroll
;         for (int u = 0; u < 4; ++u) { const int row = row0 + u * NGW; if (row < nrows) { const u32x2* xr = (const u32x2*)(x + (size_t)row * 1024) + lane;
; #pragma unroll
;                 for (int j = 0; j < 4; ++j) v[u][j] = xr[64 * j];
;                 rstd[u] = 1.f / sqrtf((float)sq[row] * (1.f / 1024.f / 16777216.f) + RMS_EPS); } }
.LBB0_371:
	s_add_i32 s22, s31, s18
	s_cmpk_lt_i32 s22, 0x4000
	s_cselect_b64 s[28:29], -1, 0
	s_cmpk_gt_i32 s22, 0x3fff
	s_cbranch_scc1 .LBB0_373
	s_ashr_i32 s23, s22, 31
	s_lshl_b64 s[6:7], s[22:23], 11
	s_lshl_b64 s[20:21], s[22:23], 3
	s_add_u32 s20, s3, s20
	s_addc_u32 s21, s13, s21
	global_load_dwordx2 v[44:45], v149, s[20:21]
	v_lshl_add_u64 v[20:21], v[6:7], 0, s[6:7]
	global_load_dwordx2 v[26:27], v[20:21], off nt
	global_load_dwordx2 v[24:25], v[20:21], off offset:512 nt
	global_load_dwordx2 v[22:23], v[20:21], off offset:1024 nt
	s_nop 0
	global_load_dwordx2 v[20:21], v[20:21], off offset:1536 nt
	s_waitcnt vmcnt(4)
	v_ffbh_u32_e32 v2, v45
	v_min_u32_e32 v2, 32, v2
	v_lshlrev_b64 v[44:45], v2, v[44:45]
	v_min_u32_e32 v44, 1, v44
	v_or_b32_e32 v44, v45, v44
	v_cvt_f32_u32_e32 v44, v44
	v_sub_u32_e32 v2, 32, v2
	v_ldexp_f32 v2, v44, v2
	v_fmamk_f32 v2, v2, 0x2e800000, v206
	v_mul_f32_e32 v44, 0x4f800000, v2
	v_cmp_gt_f32_e32 vcc, s80, v2
	s_nop 1
	v_cndmask_b32_e32 v2, v2, v44, vcc
	v_sqrt_f32_e32 v44, v2
	s_nop 0
	v_add_u32_e32 v45, -1, v44
	v_add_u32_e32 v46, 1, v44
	v_fma_f32 v47, -v45, v44, v2
	v_fma_f32 v48, -v46, v44, v2
	v_cmp_ge_f32_e64 s[6:7], 0, v47
	s_nop 1
	v_cndmask_b32_e64 v44, v44, v45, s[6:7]
	v_cmp_lt_f32_e64 s[6:7], 0, v48
	s_nop 1
	v_cndmask_b32_e64 v44, v44, v46, s[6:7]
	v_mul_f32_e32 v45, 0x37800000, v44
	v_cndmask_b32_e32 v44, v44, v45, vcc
	v_cmp_class_f32_e32 vcc, v2, v207
	s_nop 1
	v_cndmask_b32_e32 v2, v44, v2, vcc
	v_div_scale_f32 v44, s[6:7], v2, v2, 1.0
	v_rcp_f32_e32 v45, v44
	v_div_scale_f32 v46, vcc, 1.0, v2, 1.0
	v_fma_f32 v47, -v44, v45, 1.0
	v_fmac_f32_e32 v45, v47, v45
	v_mul_f32_e32 v47, v46, v45
	v_fma_f32 v48, -v44, v47, v46
	v_fmac_f32_e32 v47, v48, v45
	v_fma_f32 v44, -v44, v47, v46
	v_div_fmas_f32 v44, v44, v45, v47
	v_div_fixup_f32 v2, v44, v2, 1.0
.LBB0_373:
	s_add_i32 s20, s81, s18
	s_cmpk_lt_i32 s20, 0x4000
	s_cselect_b64 s[26:27], -1, 0
	s_cmpk_gt_i32 s20, 0x3fff
	s_cbranch_scc1 .LBB0_375
	s_ashr_i32 s21, s20, 31
	s_lshl_b64 s[6:7], s[20:21], 11
	s_lshl_b64 s[34:35], s[20:21], 3
	s_add_u32 s34, s3, s34
	s_addc_u32 s35, s13, s35
	global_load_dwordx2 v[44:45], v149, s[34:35]
	v_lshl_add_u64 v[12:13], v[6:7], 0, s[6:7]
	global_load_dwordx2 v[18:19], v[12:13], off nt
	global_load_dwordx2 v[16:17], v[12:13], off offset:512 nt
	global_load_dwordx2 v[14:15], v[12:13], off offset:1024 nt
	s_nop 0
	global_load_dwordx2 v[12:13], v[12:13], off offset:1536 nt
	s_waitcnt vmcnt(4)
	v_ffbh_u32_e32 v3, v45
	v_min_u32_e32 v3, 32, v3
	v_lshlrev_b64 v[44:45], v3, v[44:45]
	v_min_u32_e32 v44, 1, v44
	v_or_b32_e32 v44, v45, v44
	v_cvt_f32_u32_e32 v44, v44
	v_sub_u32_e32 v3, 32, v3
	v_ldexp_f32 v3, v44, v3
	v_fmamk_f32 v3, v3, 0x2e800000, v206
	v_mul_f32_e32 v44, 0x4f800000, v3
	v_cmp_gt_f32_e32 vcc, s80, v3
	s_nop 1
	v_cndmask_b32_e32 v3, v3, v44, vcc
	v_sqrt_f32_e32 v44, v3
	s_nop 0
	v_add_u32_e32 v45, -1, v44
	v_add_u32_e32 v46, 1, v44
	v_fma_f32 v47, -v45, v44, v3
	v_fma_f32 v48, -v46, v44, v3
	v_cmp_ge_f32_e64 s[6:7], 0, v47
	s_nop 1
	v_cndmask_b32_e64 v44, v44, v45, s[6:7]
	v_cmp_lt_f32_e64 s[6:7], 0, v48
	s_nop 1
	v_cndmask_b32_e64 v44, v44, v46, s[6:7]
	v_mul_f32_e32 v45, 0x37800000, v44
	v_cndmask_b32_e32 v44, v44, v45, vcc
	v_cmp_class_f32_e32 vcc, v3, v207
	s_nop 1
	v_cndmask_b32_e32 v3, v44, v3, vcc
	v_div_scale_f32 v44, s[6:7], v3, v3, 1.0
	v_rcp_f32_e32 v45, v44
	v_div_scale_f32 v46, vcc, 1.0, v3, 1.0
	v_fma_f32 v47, -v44, v45, 1.0
	v_fmac_f32_e32 v45, v47, v45
	v_mul_f32_e32 v47, v46, v45
	v_fma_f32 v48, -v44, v47, v46
	v_fmac_f32_e32 v47, v48, v45
	v_fma_f32 v44, -v44, v47, v46
	v_div_fmas_f32 v44, v44, v45, v47
	v_div_fixup_f32 v3, v44, v3, 1.0

; #define LASQ __attribute__((address_space(3)))
; #define DL_KLOAD(u) do { DL_DECODE(u); const bf16_t* kg_ = KD + ((size_t)seq * S + res) * 1536 + hh * 128 + kc_ * 8; _Pragma("unroll") for (int i = 0; i < 12; ++i) { int m_ = m0 - 64 + kr_ + 32 * i; m_ = m_ < 0 ? 0 : (m_ >= L ? L - 1 : m_); \
;         st[i] = *(const u32x4*)(kg_ + ((size_t)m_ << ds) * 1536); } } while (0)
; #define DL_KSTORE() do { _Pragma("unroll") for (int i = 0; i < 12; ++i) *(u32x4*)(kst_ + i * (32 * DL_KP)) = st[i]; } while (0)
; #define DL_VLOAD(u) do { DL_DECODE(u); const bf16_t* vg_ = VDT + ((size_t)seq * S + res) * 1536 + hh * 128 + kc_ * 8; _Pragma("unroll") for (int i = 0; i < 12; ++i) { int m_ = m0 - 64 + kr_ + 32 * i; m_ = m_ < 0 ? 0 : (m_ >= L ? L - 1 : m_); \
;         st[i] = *(const u32x4*)(vg_ + ((size_t)m_ << ds) * 1536); } } while (0)
; DI void dil_phase(unsigned char* lds, unsigned char* ws, int S, int sshift, int vcu, int G, int tid, int wave, int lane) {
;     ...
;     const int kr_ = tid >> 4, kc_ = tid & 15, vr_ = tid >> 2, vq_ = tid & 3;
;     unsigned char* const kst_ = lds + kr_ * DL_KP + kc_ * 16; (void)vr_; (void)vq_;
;     ...
;     unsigned char* const vsw_ = lds + kr_ * 256 + ((kc_ ^ ((kr_ & 3) << 2)) << 4);
;     typedef short v4i16_t __attribute__((ext_vector_type(4)));
;     LASQ unsigned char* const l3_ = (LASQ unsigned char*)lds;
;     const int i16_ = lane & 15, tq_ = i16_ >> 2, tp_ = i16_ & 3, tblk_ = (lane >> 4) & 1;
;     int u = vcu;
;     if (u < nunits) { DL_KLOAD(u); DL_KSTORE(); }
;     __syncthreads();
;     for (; u < nunits; u += G) {
;         DL_DECODE(u);
;         DL_VLOAD(u);
;         const int mq0 = m0 + 32 * wave;
;         const size_t tokq = (size_t)seq * S + ((size_t)(mq0 + r) << ds) + res;
;         const bf16_t* qp = QD + tokq * 1536 + hh * 128 + 8 * h;
;         bf16x8 qf[8];
; #pragma unroll
;         for (int s = 0; s < 8; ++s) qf[s] = *(const bf16x8*)(qp + 16 * s);
.LBB0_689:
	s_ashr_i32 s72, s15, s3
	s_mul_hi_i32 s4, s72, 0x2aaaaaab
	s_lshr_b32 s73, s4, 31
	s_ashr_i32 s4, s4, 1
	s_add_i32 s4, s4, s73
	s_mul_i32 s73, s4, 12
	s_sub_i32 s84, s72, s73
	s_ashr_i32 s94, s84, 2
	s_lshl_b32 s74, s94, 1
	s_sub_i32 s72, s33, s74
	s_and_b32 s5, s15, s2
	s_add_i32 s72, s72, -8
	s_lshr_b32 s73, s5, s72
	s_lshl_b32 s72, -1, s72
	s_andn2_b32 s5, s5, s72
	s_lshl_b32 s87, s5, 8
	s_ashr_i32 s5, s4, 31
	s_lshr_b32 s86, s93, s74
	s_lshl_b64 s[4:5], s[4:5], s33
	s_add_u32 s4, s4, s73
	s_addc_u32 s5, s5, 0
	s_mul_i32 s72, s5, 0xc00
	s_mul_hi_u32 s73, s4, 0xc00
	s_add_i32 s73, s73, s72
	s_mul_i32 s72, s4, 0xc00
	s_add_u32 s75, s12, s72
	s_addc_u32 s77, s13, s73
	s_lshl_b32 s72, s84, 7
	s_ashr_i32 s73, s72, 31
	s_lshl_b64 s[72:73], s[72:73], 1
	s_add_u32 s76, s75, s72
	s_addc_u32 s77, s77, s73
	v_add_u32_e32 v8, s87, v151
	s_add_i32 s75, s86, -1
	v_min_i32_e32 v2, s75, v8
	v_cmp_lt_i32_e32 vcc, -1, v8
	v_lshl_add_u64 v[0:1], s[76:77], 0, v[148:149]
	s_movk_i32 s16, 0xffdf
	v_cndmask_b32_e32 v2, 0, v2, vcc
	v_ashrrev_i32_e32 v3, 31, v2
	v_lshlrev_b64 v[2:3], s74, v[2:3]
	v_mad_u64_u32 v[4:5], s[76:77], v2, s91, v[0:1]
	v_mov_b32_e32 v2, v5
	v_mad_u64_u32 v[2:3], s[76:77], v3, s91, v[2:3]
	v_mov_b32_e32 v5, v2
	v_add_u32_e32 v2, 32, v8
	v_min_i32_e32 v2, s75, v2
	v_cmp_lt_i32_e32 vcc, s16, v8
	s_movk_i32 s16, 0xff9f
	v_mov_b32_e32 v184, 0xf149f2ca
	v_cndmask_b32_e32 v2, 0, v2, vcc
	v_ashrrev_i32_e32 v3, 31, v2
	v_lshlrev_b64 v[2:3], s74, v[2:3]
	v_mad_u64_u32 v[6:7], s[76:77], v2, s91, v[0:1]
	v_mov_b32_e32 v2, v7
	v_mad_u64_u32 v[2:3], s[76:77], v3, s91, v[2:3]
	v_mov_b32_e32 v7, v2
	v_add_u32_e32 v2, s87, v146
	v_min_i32_e32 v3, s75, v2
	v_cmp_lt_i32_e32 vcc, -1, v2
	global_load_dwordx4 v[64:67], v[4:5], off
	global_load_dwordx4 v[68:71], v[6:7], off
	v_cndmask_b32_e32 v2, 0, v3, vcc
	v_ashrrev_i32_e32 v3, 31, v2
	v_lshlrev_b64 v[2:3], s74, v[2:3]
	v_mad_u64_u32 v[4:5], s[76:77], v2, s91, v[0:1]
	v_mov_b32_e32 v2, v5
	v_mad_u64_u32 v[2:3], s[76:77], v3, s91, v[2:3]
	v_mov_b32_e32 v5, v2
	v_add_u32_e32 v2, 0x60, v8
	v_min_i32_e32 v2, s75, v2
	v_cmp_lt_i32_e32 vcc, s16, v8
	s_movk_i32 s16, 0xff7f
	s_add_i32 s87, s87, s14
	v_cndmask_b32_e32 v2, 0, v2, vcc
	v_ashrrev_i32_e32 v3, 31, v2
	v_lshlrev_b64 v[2:3], s74, v[2:3]
	v_mad_u64_u32 v[6:7], s[76:77], v2, s91, v[0:1]
	v_mov_b32_e32 v2, v7
	v_mad_u64_u32 v[2:3], s[76:77], v3, s91, v[2:3]
	v_mov_b32_e32 v7, v2
	v_add_u32_e32 v2, 0x80, v8
	v_min_i32_e32 v2, s75, v2
	v_cmp_lt_i32_e32 vcc, s16, v8
	global_load_dwordx4 v[72:75], v[4:5], off
	global_load_dwordx4 v[76:79], v[6:7], off
	v_cndmask_b32_e32 v2, 0, v2, vcc
	v_ashrrev_i32_e32 v3, 31, v2
	v_lshlrev_b64 v[2:3], s74, v[2:3]
	v_mad_u64_u32 v[4:5], s[76:77], v2, s91, v[0:1]
	v_mov_b32_e32 v2, v5
	v_mad_u64_u32 v[2:3], s[76:77], v3, s91, v[2:3]
	v_mov_b32_e32 v5, v2
	v_add_u32_e32 v2, 0xa0, v8
	s_movk_i32 s16, 0xff5f
	v_min_i32_e32 v2, s75, v2
	v_cmp_lt_i32_e32 vcc, s16, v8
	s_movk_i32 s16, 0xff3f
	v_mov_b32_e32 v179, 0xf149f2ca
	v_cndmask_b32_e32 v2, 0, v2, vcc
	v_ashrrev_i32_e32 v3, 31, v2
	v_lshlrev_b64 v[2:3], s74, v[2:3]
	v_mad_u64_u32 v[6:7], s[76:77], v2, s91, v[0:1]
	v_mov_b32_e32 v2, v7
	v_mad_u64_u32 v[2:3], s[76:77], v3, s91, v[2:3]
	v_mov_b32_e32 v7, v2
	v_add_u32_e32 v2, 0xc0, v8
	v_min_i32_e32 v2, s75, v2
	v_cmp_lt_i32_e32 vcc, s16, v8
	global_load_dwordx4 v[80:83], v[4:5], off
	global_load_dwordx4 v[84:87], v[6:7], off
	v_cndmask_b32_e32 v2, 0, v2, vcc
	v_ashrrev_i32_e32 v3, 31, v2
	v_lshlrev_b64 v[2:3], s74, v[2:3]
	v_mad_u64_u32 v[4:5], s[76:77], v2, s91, v[0:1]
	v_mov_b32_e32 v2, v5
	v_mad_u64_u32 v[2:3], s[76:77], v3, s91, v[2:3]
	v_mov_b32_e32 v5, v2
	v_add_u32_e32 v2, 0xe0, v8
	s_movk_i32 s16, 0xff1f
	v_min_i32_e32 v2, s75, v2
	v_cmp_lt_i32_e32 vcc, s16, v8
	s_movk_i32 s16, 0xfeff
	v_mov_b32_e32 v181, 0xf149f2ca
	v_cndmask_b32_e32 v2, 0, v2, vcc
	v_ashrrev_i32_e32 v3, 31, v2
	v_lshlrev_b64 v[2:3], s74, v[2:3]
	v_mad_u64_u32 v[6:7], s[76:77], v2, s91, v[0:1]
	v_mov_b32_e32 v2, v7
	v_mad_u64_u32 v[2:3], s[76:77], v3, s91, v[2:3]
	v_mov_b32_e32 v7, v2
	v_add_u32_e32 v2, 0x100, v8
	v_min_i32_e32 v2, s75, v2
	v_cmp_lt_i32_e32 vcc, s16, v8
	global_load_dwordx4 v[88:91], v[4:5], off
	global_load_dwordx4 v[92:95], v[6:7], off
	v_cndmask_b32_e32 v2, 0, v2, vcc
	v_ashrrev_i32_e32 v3, 31, v2
	v_lshlrev_b64 v[2:3], s74, v[2:3]
	v_mad_u64_u32 v[4:5], s[76:77], v2, s91, v[0:1]
	v_mov_b32_e32 v2, v5
	v_mad_u64_u32 v[2:3], s[76:77], v3, s91, v[2:3]
	v_mov_b32_e32 v5, v2
	v_add_u32_e32 v2, 0x120, v8
	s_movk_i32 s16, 0xfedf
	v_min_i32_e32 v2, s75, v2
	v_cmp_lt_i32_e32 vcc, s16, v8
	s_movk_i32 s16, 0xfebf
	v_mov_b32_e32 v182, 0xf149f2ca
	v_cndmask_b32_e32 v2, 0, v2, vcc
	v_ashrrev_i32_e32 v3, 31, v2
	v_lshlrev_b64 v[2:3], s74, v[2:3]
	v_mad_u64_u32 v[6:7], s[76:77], v2, s91, v[0:1]
	v_mov_b32_e32 v2, v7
	v_mad_u64_u32 v[2:3], s[76:77], v3, s91, v[2:3]
	v_mov_b32_e32 v7, v2
	v_add_u32_e32 v2, 0x140, v8
	v_min_i32_e32 v2, s75, v2
	v_cmp_lt_i32_e32 vcc, s16, v8
	global_load_dwordx4 v[96:99], v[4:5], off
	global_load_dwordx4 v[100:103], v[6:7], off
	v_cndmask_b32_e32 v2, 0, v2, vcc
; #define MFMA32(a, b, c) __builtin_amdgcn_mfma_f32_32x32x16_bf16((a), (b), (c), 0, 0, 0)
; DI float vmax16(const f32x16& s) { return fmaxf(fmaxf(fmaxf(fmaxf(s[0], s[1]), fmaxf(s[2], s[3])), fmaxf(fmaxf(s[4], s[5]), fmaxf(s[6], s[7]))), fmaxf(fmaxf(fmaxf(s[8], s[9]), fmaxf(s[10], s[11])), fmaxf(fmaxf(s[12], s[13]), fmaxf(s[14], s[15])))); }
; DI void dil_phase(unsigned char* lds, unsigned char* ws, int S, int sshift, int vcu, int G, int tid, int wave, int lane) {
;     ...
;         const size_t tokq = (size_t)seq * S + ((size_t)(mq0 + r) << ds) + res;
;         const bf16_t* qp = QD + tokq * 1536 + hh * 128 + 8 * h;
;         bf16x8 qf[8];
; #pragma unroll
;         for (int s = 0; s < 8; ++s) qf[s] = *(const bf16x8*)(qp + 16 * s);
;         f32x16 sc[5]; float mx = -1e30f;
; #pragma unroll
;         for (int j = 0; j < 5; ++j) {
;             const int mk0 = mq0 - 64 + 32 * j;
;             sc[j] = zero16();
;             if (mk0 >= 0 && mk0 < L) {
;                 const unsigned char* kb = lds + (32 * wave + 32 * j + r) * DL_KP + 16 * h;
;                 bf16x8 kf[4];
; #pragma unroll
;                 for (int s = 0; s < 4; ++s) kf[s] = *(const bf16x8*)(kb + 32 * s);
; #pragma unroll
;                 for (int s = 0; s < 4; ++s) sc[j] = MFMA32(kf[s], qf[s], sc[j]);
; #pragma unroll
;                 for (int s = 0; s < 4; ++s) kf[s] = *(const bf16x8*)(kb + 128 + 32 * s);
; #pragma unroll
;                 for (int s = 0; s < 4; ++s) sc[j] = MFMA32(kf[s], qf[4 + s], sc[j]);
;                 if (j == 0 || j == 4) {
; #pragma unroll
;                     for (int i = 0; i < 16; ++i) { const int kr = (i & 3) + 8 * (i >> 2) + 4 * h; const bool ok = (j == 0) ? (kr >= r) : (kr <= r); sc[j][i] = ok ? sc[j][i] : -1e30f; }
;                 }
;                 mx = fmaxf(mx, vmax16(sc[j]));
	v_ashrrev_i32_e32 v3, 31, v2
	v_lshlrev_b64 v[2:3], s74, v[2:3]
	v_mad_u64_u32 v[4:5], s[76:77], v2, s91, v[0:1]
	v_mov_b32_e32 v2, v5
	v_mad_u64_u32 v[2:3], s[76:77], v3, s91, v[2:3]
	v_mov_b32_e32 v5, v2
	v_add_u32_e32 v2, 0x160, v8
	s_movk_i32 s16, 0xfe9f
	v_min_i32_e32 v2, s75, v2
	v_cmp_lt_i32_e32 vcc, s16, v8
	v_mov_b32_e32 v183, 0xf149f2ca
	v_mov_b32_e32 v176, 0xf149f2ca
	v_cndmask_b32_e32 v2, 0, v2, vcc
	v_ashrrev_i32_e32 v3, 31, v2
	v_lshlrev_b64 v[2:3], s74, v[2:3]
	v_mad_u64_u32 v[0:1], s[76:77], v2, s91, v[0:1]
	v_mov_b32_e32 v2, v1
	v_mad_u64_u32 v[2:3], s[76:77], v3, s91, v[2:3]
	v_mov_b32_e32 v1, v2
	global_load_dwordx4 v[104:107], v[4:5], off
	global_load_dwordx4 v[108:111], v[0:1], off
	v_or_b32_e32 v0, s87, v156
	v_ashrrev_i32_e32 v1, 31, v0
	v_lshlrev_b64 v[0:1], s74, v[0:1]
	v_lshl_add_u64 v[144:145], v[0:1], 0, s[4:5]
	v_mov_b64_e32 v[0:1], s[88:89]
	v_mad_u64_u32 v[0:1], s[4:5], v144, s91, v[0:1]
	v_mov_b32_e32 v2, v1
	v_mad_u64_u32 v[2:3], s[4:5], v145, s91, v[2:3]
	v_mov_b32_e32 v1, v2
	v_lshl_add_u64 v[0:1], v[0:1], 0, s[72:73]
	v_lshl_add_u64 v[0:1], v[140:141], 1, v[0:1]
	global_load_dwordx4 v[48:51], v[0:1], off nt
	global_load_dwordx4 v[136:139], v[0:1], off offset:32 nt
	global_load_dwordx4 v[132:135], v[0:1], off offset:64 nt
	global_load_dwordx4 v[128:131], v[0:1], off offset:96 nt
	global_load_dwordx4 v[124:127], v[0:1], off offset:128 nt
	global_load_dwordx4 v[120:123], v[0:1], off offset:160 nt
	global_load_dwordx4 v[116:119], v[0:1], off offset:192 nt
	global_load_dwordx4 v[112:115], v[0:1], off offset:224 nt
	s_sub_i32 s72, s87, 64
	s_cmp_gt_i32 s87, 63
	s_cselect_b64 s[4:5], -1, 0
	s_cmp_lt_i32 s72, s86
	s_cselect_b64 s[72:73], -1, 0
	s_and_b64 s[4:5], s[4:5], s[72:73]
	v_cndmask_b32_e64 v1, 0, 1, s[4:5]
	v_mov_b32_e32 v0, 0xf149f2ca
	v_cmp_ne_u32_e64 s[80:81], 1, v1
	s_andn2_b64 vcc, exec, s[4:5]
	v_mov_b32_e32 v177, 0xf149f2ca
	v_mov_b32_e32 v180, 0xf149f2ca
	v_mov_b32_e32 v178, 0xf149f2ca
	v_mov_b32_e32 v175, 0xf149f2ca
	v_mov_b32_e32 v174, 0xf149f2ca
	v_mov_b32_e32 v173, 0xf149f2ca
	v_mov_b32_e32 v172, 0xf149f2ca
	v_mov_b32_e32 v171, 0xf149f2ca
	v_mov_b32_e32 v170, 0xf149f2ca
	v_mov_b32_e32 v169, 0xf149f2ca
	v_mov_b32_e32 v168, 0xf149f2ca
	s_cbranch_vccnz .LBB0_691
	ds_read_b128 v[2:5], v163
	ds_read_b128 v[18:21], v163 offset:32
	v_readlane_b32 s4, v254, 46
	v_readlane_b32 s5, v254, 47
	s_waitcnt vmcnt(7) lgkmcnt(1)
	v_mfma_f32_32x32x16_bf16 v[2:17], v[2:5], v[48:51], 0
	s_waitcnt vmcnt(6) lgkmcnt(0)
	v_mfma_f32_32x32x16_bf16 v[2:17], v[18:21], v[136:139], v[2:17]
	ds_read_b128 v[18:21], v163 offset:64
	s_waitcnt vmcnt(5) lgkmcnt(0)
	v_mfma_f32_32x32x16_bf16 v[2:17], v[18:21], v[132:135], v[2:17]
	ds_read_b128 v[18:21], v163 offset:96
	s_waitcnt vmcnt(4) lgkmcnt(0)
	v_mfma_f32_32x32x16_bf16 v[2:17], v[18:21], v[128:131], v[2:17]
	ds_read_b128 v[18:21], v163 offset:128
	s_waitcnt vmcnt(3) lgkmcnt(0)
	v_mfma_f32_32x32x16_bf16 v[2:17], v[18:21], v[124:127], v[2:17]
	ds_read_b128 v[18:21], v163 offset:160
	s_waitcnt vmcnt(2) lgkmcnt(0)
	v_mfma_f32_32x32x16_bf16 v[2:17], v[18:21], v[120:123], v[2:17]
	ds_read_b128 v[18:21], v163 offset:192
	s_waitcnt vmcnt(1) lgkmcnt(0)
	v_mfma_f32_32x32x16_bf16 v[2:17], v[18:21], v[116:119], v[2:17]
	ds_read_b128 v[18:21], v163 offset:224
	s_waitcnt vmcnt(0) lgkmcnt(0)
	v_mfma_f32_32x32x16_bf16 v[2:17], v[18:21], v[112:115], v[2:17]
	s_nop 11
	v_cndmask_b32_e64 v181, v3, v214, s[4:5]
	v_readlane_b32 s4, v254, 48
	v_readlane_b32 s5, v254, 49
	v_cndmask_b32_e64 v179, v2, v214, s[8:9]
	v_cndmask_b32_e64 v178, v9, v214, s[22:23]
	v_cndmask_b32_e64 v182, v4, v214, s[4:5]
	v_readlane_b32 s4, v254, 50
	v_readlane_b32 s5, v254, 51
	v_cndmask_b32_e64 v169, v16, v214, s[38:39]
	v_cndmask_b32_e64 v168, v17, v214, s[40:41]
	v_cndmask_b32_e64 v183, v5, v214, s[4:5]
	v_readlane_b32 s4, v254, 52
	v_readlane_b32 s5, v254, 53
	v_cndmask_b32_e64 v175, v10, v214, s[24:25]
	v_cndmask_b32_e64 v174, v11, v214, s[26:27]
	v_cndmask_b32_e64 v176, v6, v214, s[4:5]
	v_readlane_b32 s4, v254, 54
	v_readlane_b32 s5, v254, 55
	v_cndmask_b32_e64 v173, v12, v214, s[28:29]
	v_cndmask_b32_e64 v172, v13, v214, s[30:31]
	v_cndmask_b32_e64 v177, v7, v214, s[4:5]
	v_readlane_b32 s4, v254, 56
	v_readlane_b32 s5, v254, 57
	v_max_f32_e32 v1, v181, v181
	v_max_f32_e32 v2, v179, v179
	v_cndmask_b32_e64 v180, v8, v214, s[4:5]
	v_max_f32_e32 v3, v183, v183
	v_max_f32_e32 v4, v182, v182
	v_max_f32_e32 v5, v178, v178
	v_max_f32_e32 v6, v180, v180
	v_max_f32_e32 v11, v168, v168
	v_max_f32_e32 v12, v169, v169
	v_cndmask_b32_e64 v171, v14, v214, s[34:35]
	v_cndmask_b32_e64 v170, v15, v214, s[36:37]
	v_max_f32_e32 v7, v174, v174
	v_max_f32_e32 v8, v175, v175
	v_max_f32_e32 v9, v172, v172
	v_max_f32_e32 v10, v173, v173
	v_max_f32_e32 v1, v2, v1
	v_max_f32_e32 v2, v4, v3
	v_max_f32_e32 v3, v6, v5
	v_max_f32_e32 v6, v12, v11
	v_max_f32_e32 v4, v8, v7
	v_max_f32_e32 v5, v10, v9
	v_max3_f32 v3, v176, v177, v3
	v_max3_f32 v6, v171, v170, v6
	v_max3_f32 v1, v1, v2, v3
	v_max3_f32 v2, v4, v5, v6
	s_mov_b32 s4, 0xf149f2ca
	v_max3_f32 v184, v1, v2, s4

; DI void t2_rows(unsigned char* ws, int gw, int NGW, int lane) {
;     ...
;     for (int t0 = gw; t0 < TCH; t0 += 2 * NGW) {
;         u32x4 raw[2][3]; float ls[2][3];
; #pragma unroll
;         for (int u = 0; u < 2; ++u) { const int t = t0 + u * NGW; if (t < TCH) {
; #pragma unroll
;                 for (int gq = 0; gq < 3; ++gq) { ls[u][gq] = LSE[((size_t)gq * TCH + t) * 4 + head]; raw[u][gq] = *(const u32x4*)(OG + ((size_t)gq * TCH + t) * 512 + lane * 8); } } }
.LBB0_998:
	s_ashr_i32 s9, s8, 31
	s_lshl_b64 s[6:7], s[8:9], 10
	v_lshl_add_u64 v[14:15], v[28:29], 0, s[6:7]
	s_add_u32 s6, s8, 0x4000
	s_addc_u32 s7, s9, 0
	v_lshl_add_u64 v[12:13], s[8:9], 4, v[26:27]
	v_lshl_add_u64 v[16:17], s[6:7], 4, v[26:27]
	s_lshl_b64 s[6:7], s[6:7], 10
	global_load_dword v35, v[12:13], off nt
	s_nop 0
	global_load_dwordx4 v[12:15], v[14:15], off nt
	s_nop 0
	global_load_dword v36, v[16:17], off nt
	v_lshl_add_u64 v[16:17], v[28:29], 0, s[6:7]
	s_add_u32 s6, s8, 0x8000
	s_addc_u32 s7, s9, 0
	v_lshl_add_u64 v[20:21], s[6:7], 4, v[26:27]
	s_lshl_b64 s[6:7], s[6:7], 10
	global_load_dwordx4 v[16:19], v[16:17], off nt
	s_nop 0
	global_load_dword v37, v[20:21], off nt
	v_lshl_add_u64 v[20:21], v[28:29], 0, s[6:7]
	global_load_dwordx4 v[20:23], v[20:21], off nt
	s_add_i32 s6, s8, s94
	s_cmpk_lt_i32 s6, 0x4000
	s_cselect_b64 s[10:11], -1, 0
	s_cmpk_gt_i32 s6, 0x3fff
	s_cbranch_scc1 .LBB0_1000
	s_ashr_i32 s7, s6, 31
	s_lshl_b64 s[12:13], s[6:7], 10
	v_lshl_add_u64 v[2:3], v[28:29], 0, s[12:13]
	s_add_u32 s12, s6, 0x4000
	s_addc_u32 s13, s7, 0
	v_lshl_add_u64 v[0:1], s[6:7], 4, v[26:27]
	v_lshl_add_u64 v[4:5], s[12:13], 4, v[26:27]
	s_lshl_b64 s[12:13], s[12:13], 10
	global_load_dword v32, v[0:1], off nt
	s_nop 0
	global_load_dwordx4 v[0:3], v[2:3], off nt
	s_nop 0
	global_load_dword v33, v[4:5], off nt
	v_lshl_add_u64 v[4:5], v[28:29], 0, s[12:13]
	s_add_u32 s12, s6, 0x8000
	s_addc_u32 s13, s7, 0
	v_lshl_add_u64 v[8:9], s[12:13], 4, v[26:27]
	s_lshl_b64 s[12:13], s[12:13], 10
	global_load_dwordx4 v[4:7], v[4:5], off nt
	s_nop 0
	global_load_dword v34, v[8:9], off nt
	v_lshl_add_u64 v[8:9], v[28:29], 0, s[12:13]
	global_load_dwordx4 v[8:11], v[8:9], off nt

; DI void final_rows(const bf16_t* x, const sq_t* sq, const float* g, float* out, int nrows, int gw, int NGW, int lane) {
;     for (int row0 = gw; row0 < nrows; row0 += 4 * NGW) {
;         u32x2 v[4][4]; float rstd[4];
; #pragma unroll
;         for (int u = 0; u < 4; ++u) { const int row = row0 + u * NGW; if (row < nrows) { const u32x2* xr = (const u32x2*)(x + (size_t)row * 1024) + lane;
; #pragma unroll
;                 for (int j = 0; j < 4; ++j) v[u][j] = xr[64 * j];
;                 rstd[u] = 1.f / sqrtf((float)sq[row] * (1.f / 1024.f / 16777216.f) + RMS_EPS); } }
.LBB0_1540:
	s_ashr_i32 s13, s12, 31
	s_lshl_b64 s[0:1], s[12:13], 11
	s_lshl_b64 s[6:7], s[12:13], 3
	s_add_u32 s8, s20, s6
	s_addc_u32 s9, s21, s7
	global_load_dwordx2 v[46:47], v42, s[8:9]
	v_lshl_add_u64 v[34:35], v[4:5], 0, s[0:1]
	global_load_dwordx2 v[40:41], v[34:35], off nt
	global_load_dwordx2 v[38:39], v[34:35], off offset:512 nt
	global_load_dwordx2 v[36:37], v[34:35], off offset:1024 nt
	s_nop 0
	global_load_dwordx2 v[34:35], v[34:35], off offset:1536 nt
	s_add_i32 s6, s12, s94
	s_cmpk_lt_i32 s6, 0x4000
	s_cselect_b64 s[18:19], -1, 0
	s_cmpk_gt_i32 s6, 0x3fff
	s_waitcnt vmcnt(0)
	v_ffbh_u32_e32 v0, v47
	v_min_u32_e32 v0, 32, v0
	v_lshlrev_b64 v[46:47], v0, v[46:47]
	v_min_u32_e32 v45, 1, v46
	v_or_b32_e32 v45, v47, v45
	v_cvt_f32_u32_e32 v45, v45
	v_sub_u32_e32 v0, 32, v0
	v_ldexp_f32 v0, v45, v0
	v_fmamk_f32 v0, v0, 0x2e800000, v43
	v_mul_f32_e32 v45, 0x4f800000, v0
	v_cmp_gt_f32_e32 vcc, s22, v0
	s_nop 1
	v_cndmask_b32_e32 v0, v0, v45, vcc
	v_sqrt_f32_e32 v45, v0
	s_nop 0
	v_add_u32_e32 v46, -1, v45
	v_add_u32_e32 v47, 1, v45
	v_fma_f32 v48, -v46, v45, v0
	v_fma_f32 v49, -v47, v45, v0
	v_cmp_ge_f32_e64 s[0:1], 0, v48
	s_nop 1
	v_cndmask_b32_e64 v45, v45, v46, s[0:1]
	v_cmp_lt_f32_e64 s[0:1], 0, v49
	s_nop 1
	v_cndmask_b32_e64 v45, v45, v47, s[0:1]
	v_mul_f32_e32 v46, 0x37800000, v45
	v_cndmask_b32_e32 v45, v45, v46, vcc
	v_cmp_class_f32_e32 vcc, v0, v44
	s_nop 1
	v_cndmask_b32_e32 v0, v45, v0, vcc
	v_div_scale_f32 v45, s[0:1], v0, v0, 1.0
	v_rcp_f32_e32 v46, v45
	v_div_scale_f32 v47, vcc, 1.0, v0, 1.0
	v_fma_f32 v48, -v45, v46, 1.0
	v_fmac_f32_e32 v46, v48, v46
	v_mul_f32_e32 v48, v47, v46
	v_fma_f32 v49, -v45, v48, v47
	v_fmac_f32_e32 v48, v49, v46
	v_fma_f32 v45, -v45, v48, v47
	v_div_fmas_f32 v45, v45, v46, v48
	v_div_fixup_f32 v0, v45, v0, 1.0
	s_cbranch_scc1 .LBB0_1542
	s_ashr_i32 s7, s6, 31
	s_lshl_b64 s[0:1], s[6:7], 11
	v_lshl_add_u64 v[30:31], v[4:5], 0, s[0:1]
	s_add_u32 s0, s8, s4
	s_addc_u32 s1, s9, s5
	global_load_dwordx2 v[24:25], v[30:31], off offset:512 nt
	global_load_dwordx2 v[22:23], v[30:31], off offset:1024 nt
	global_load_dwordx2 v[46:47], v42, s[0:1]
	global_load_dwordx2 v[32:33], v[30:31], off nt
	s_nop 0
	global_load_dwordx2 v[30:31], v[30:31], off offset:1536 nt
	s_waitcnt vmcnt(2)
	v_ffbh_u32_e32 v1, v47
	v_min_u32_e32 v1, 32, v1
	v_lshlrev_b64 v[46:47], v1, v[46:47]
	v_min_u32_e32 v45, 1, v46
	v_or_b32_e32 v45, v47, v45
	v_cvt_f32_u32_e32 v45, v45
	v_sub_u32_e32 v1, 32, v1
	v_ldexp_f32 v1, v45, v1
	v_fmamk_f32 v1, v1, 0x2e800000, v43
	v_mul_f32_e32 v45, 0x4f800000, v1
	v_cmp_gt_f32_e32 vcc, s22, v1
	s_nop 1
	v_cndmask_b32_e32 v1, v1, v45, vcc
	v_sqrt_f32_e32 v45, v1
	s_nop 0
	v_add_u32_e32 v46, -1, v45
	v_add_u32_e32 v47, 1, v45
	v_fma_f32 v48, -v46, v45, v1
	v_fma_f32 v49, -v47, v45, v1
	v_cmp_ge_f32_e64 s[0:1], 0, v48
	s_nop 1
	v_cndmask_b32_e64 v45, v45, v46, s[0:1]
	v_cmp_lt_f32_e64 s[0:1], 0, v49
	s_nop 1
	v_cndmask_b32_e64 v45, v45, v47, s[0:1]
	v_mul_f32_e32 v46, 0x37800000, v45
	v_cndmask_b32_e32 v45, v45, v46, vcc
	v_cmp_class_f32_e32 vcc, v1, v44
	s_nop 1
	v_cndmask_b32_e32 v1, v45, v1, vcc
	v_div_scale_f32 v45, s[0:1], v1, v1, 1.0
	v_rcp_f32_e32 v46, v45
	v_div_scale_f32 v47, vcc, 1.0, v1, 1.0
	v_fma_f32 v48, -v45, v46, 1.0
	v_fmac_f32_e32 v46, v48, v46
	v_mul_f32_e32 v48, v47, v46
	v_fma_f32 v49, -v45, v48, v47
	v_fmac_f32_e32 v48, v49, v46
	v_fma_f32 v45, -v45, v48, v47
	v_div_fmas_f32 v45, v45, v46, v48
	v_div_fixup_f32 v1, v45, v1, 1.0
; DI void final_rows(const bf16_t* x, const sq_t* sq, const float* g, float* out, int nrows, int gw, int NGW, int lane) {
;     for (int row0 = gw; row0 < nrows; row0 += 4 * NGW) {
;         u32x2 v[4][4]; float rstd[4];
; #pragma unroll
;         for (int u = 0; u < 4; ++u) { const int row = row0 + u * NGW; if (row < nrows) { const u32x2* xr = (const u32x2*)(x + (size_t)row * 1024) + lane;
; #pragma unroll
;                 for (int j = 0; j < 4; ++j) v[u][j] = xr[64 * j];
;                 rstd[u] = 1.f / sqrtf((float)sq[row] * (1.f / 1024.f / 16777216.f) + RMS_EPS); } }
.LBB0_1542:
	s_add_i32 s10, s23, s12
	s_cmpk_lt_i32 s10, 0x4000
	s_cselect_b64 s[16:17], -1, 0
	s_cmpk_gt_i32 s10, 0x3fff
	s_cbranch_scc1 .LBB0_1544
	s_ashr_i32 s11, s10, 31
	s_lshl_b64 s[0:1], s[10:11], 11
	v_lshl_add_u64 v[26:27], v[4:5], 0, s[0:1]
	s_lshl_b64 s[0:1], s[10:11], 3
	s_add_u32 s0, s20, s0
	s_addc_u32 s1, s21, s1
	global_load_dwordx2 v[16:17], v[26:27], off offset:512 nt
	global_load_dwordx2 v[14:15], v[26:27], off offset:1024 nt
	global_load_dwordx2 v[46:47], v42, s[0:1]
	global_load_dwordx2 v[28:29], v[26:27], off nt
	s_nop 0
	global_load_dwordx2 v[26:27], v[26:27], off offset:1536 nt
	s_waitcnt vmcnt(2)
	v_ffbh_u32_e32 v2, v47
	v_min_u32_e32 v2, 32, v2
	v_lshlrev_b64 v[46:47], v2, v[46:47]
	v_min_u32_e32 v45, 1, v46
	v_or_b32_e32 v45, v47, v45
	v_cvt_f32_u32_e32 v45, v45
	v_sub_u32_e32 v2, 32, v2
	v_ldexp_f32 v2, v45, v2
	v_fmamk_f32 v2, v2, 0x2e800000, v43
	v_mul_f32_e32 v45, 0x4f800000, v2
	v_cmp_gt_f32_e32 vcc, s22, v2
	s_nop 1
	v_cndmask_b32_e32 v2, v2, v45, vcc
	v_sqrt_f32_e32 v45, v2
	s_nop 0
	v_add_u32_e32 v46, -1, v45
	v_add_u32_e32 v47, 1, v45
	v_fma_f32 v48, -v46, v45, v2
	v_fma_f32 v49, -v47, v45, v2
	v_cmp_ge_f32_e64 s[0:1], 0, v48
	s_nop 1
	v_cndmask_b32_e64 v45, v45, v46, s[0:1]
	v_cmp_lt_f32_e64 s[0:1], 0, v49
	s_nop 1
	v_cndmask_b32_e64 v45, v45, v47, s[0:1]
	v_mul_f32_e32 v46, 0x37800000, v45
	v_cndmask_b32_e32 v45, v45, v46, vcc
	v_cmp_class_f32_e32 vcc, v2, v44
	s_nop 1
	v_cndmask_b32_e32 v2, v45, v2, vcc
	v_div_scale_f32 v45, s[0:1], v2, v2, 1.0
	v_rcp_f32_e32 v46, v45
	v_div_scale_f32 v47, vcc, 1.0, v2, 1.0
	v_fma_f32 v48, -v45, v46, 1.0
	v_fmac_f32_e32 v46, v48, v46
	v_mul_f32_e32 v48, v47, v46
	v_fma_f32 v49, -v45, v48, v47
	v_fmac_f32_e32 v48, v49, v46
	v_fma_f32 v45, -v45, v48, v47
	v_div_fmas_f32 v45, v45, v46, v48
	v_div_fixup_f32 v2, v45, v2, 1.0
.LBB0_1544:
	s_add_i32 s8, s81, s12
	s_cmpk_lt_i32 s8, 0x4000
	s_cselect_b64 s[14:15], -1, 0
	s_cmpk_gt_i32 s8, 0x3fff
	s_cbranch_scc1 .LBB0_1546
	s_ashr_i32 s9, s8, 31
	s_lshl_b64 s[0:1], s[8:9], 11
	v_lshl_add_u64 v[18:19], v[4:5], 0, s[0:1]
	s_lshl_b64 s[0:1], s[8:9], 3
	s_add_u32 s0, s20, s0
	s_addc_u32 s1, s21, s1
	global_load_dwordx2 v[12:13], v[18:19], off offset:512 nt
	global_load_dwordx2 v[10:11], v[18:19], off offset:1024 nt
	global_load_dwordx2 v[46:47], v42, s[0:1]
	global_load_dwordx2 v[20:21], v[18:19], off nt
	s_nop 0
	global_load_dwordx2 v[18:19], v[18:19], off offset:1536 nt
	s_waitcnt vmcnt(2)
	v_ffbh_u32_e32 v3, v47
	v_min_u32_e32 v3, 32, v3
	v_lshlrev_b64 v[46:47], v3, v[46:47]
	v_min_u32_e32 v45, 1, v46
	v_or_b32_e32 v45, v47, v45
	v_cvt_f32_u32_e32 v45, v45
	v_sub_u32_e32 v3, 32, v3
	v_ldexp_f32 v3, v45, v3
	v_fmamk_f32 v3, v3, 0x2e800000, v43
	v_mul_f32_e32 v45, 0x4f800000, v3
	v_cmp_gt_f32_e32 vcc, s22, v3
	s_nop 1
	v_cndmask_b32_e32 v3, v3, v45, vcc
	v_sqrt_f32_e32 v45, v3
	s_nop 0
	v_add_u32_e32 v46, -1, v45
	v_add_u32_e32 v47, 1, v45
	v_fma_f32 v48, -v46, v45, v3
	v_fma_f32 v49, -v47, v45, v3
	v_cmp_ge_f32_e64 s[0:1], 0, v48
	s_nop 1
	v_cndmask_b32_e64 v45, v45, v46, s[0:1]
	v_cmp_lt_f32_e64 s[0:1], 0, v49
	s_nop 1
	v_cndmask_b32_e64 v45, v45, v47, s[0:1]
	v_mul_f32_e32 v46, 0x37800000, v45
	v_cndmask_b32_e32 v45, v45, v46, vcc
	v_cmp_class_f32_e32 vcc, v3, v44
	s_nop 1
	v_cndmask_b32_e32 v3, v45, v3, vcc
	v_div_scale_f32 v45, s[0:1], v3, v3, 1.0
	v_rcp_f32_e32 v46, v45
	v_div_scale_f32 v47, vcc, 1.0, v3, 1.0
	v_fma_f32 v48, -v45, v46, 1.0
	v_fmac_f32_e32 v46, v48, v46
	v_mul_f32_e32 v48, v47, v46
	v_fma_f32 v49, -v45, v48, v47
	v_fmac_f32_e32 v48, v49, v46
	v_fma_f32 v45, -v45, v48, v47
	v_div_fmas_f32 v45, v45, v46, v48
	v_div_fixup_f32 v3, v45, v3, 1.0
